# P1 (memory K/V projection) GEMM: leading wave half runs its epilogue during the trailing half's last MFMA block (align barrier after the epilogue)
# baseline (speedup 1.0000x reference)
.LBB0_123:
	v_lshl_add_u32 v154, s30, 8, v147
	v_lshl_or_b32 v144, s68, 8, v149
	v_ashrrev_i32_e32 v155, 31, v154
	v_ashrrev_i32_e32 v145, 31, v144
	v_lshlrev_b64 v[156:157], 13, v[154:155]
	v_lshl_add_u64 v[156:157], s[6:7], 0, v[156:157]
	v_lshlrev_b64 v[158:159], 1, v[144:145]
	v_lshl_add_u64 v[144:145], v[156:157], 0, v[158:159]
	v_cvt_pk_bf16_f32 v124, v124, v125
	v_cvt_pk_bf16_f32 v125, v126, v127
	v_cvt_pk_bf16_f32 v126, v120, v121
	v_cvt_pk_bf16_f32 v127, v122, v123
	global_store_dwordx4 v[144:145], v[124:127], off
	v_cvt_pk_bf16_f32 v112, v112, v113
	v_cvt_pk_bf16_f32 v113, v114, v115
	v_cvt_pk_bf16_f32 v114, v104, v105
	v_or_b32_e32 v104, 16, v154
	v_ashrrev_i32_e32 v105, 31, v104
	v_lshlrev_b64 v[104:105], 13, v[104:105]
	v_lshl_add_u64 v[104:105], s[6:7], 0, v[104:105]
	v_cvt_pk_bf16_f32 v115, v106, v107
	global_store_dwordx4 v[144:145], v[112:115], off offset:256
	s_nop 1
	v_lshl_add_u64 v[112:113], v[104:105], 0, v[158:159]
	v_cvt_pk_bf16_f32 v104, v116, v117
	v_cvt_pk_bf16_f32 v105, v118, v119
	v_cvt_pk_bf16_f32 v106, v108, v109
	v_cvt_pk_bf16_f32 v107, v110, v111
	global_store_dwordx4 v[112:113], v[104:107], off
	v_cvt_pk_bf16_f32 v96, v96, v97
	v_cvt_pk_bf16_f32 v97, v98, v99
	v_cvt_pk_bf16_f32 v98, v88, v89
	v_or_b32_e32 v88, 32, v154
	v_ashrrev_i32_e32 v89, 31, v88
	v_lshlrev_b64 v[88:89], 13, v[88:89]
	v_lshl_add_u64 v[88:89], s[6:7], 0, v[88:89]
	v_cvt_pk_bf16_f32 v99, v90, v91
	global_store_dwordx4 v[112:113], v[96:99], off offset:256
	s_nop 1
	v_lshl_add_u64 v[96:97], v[88:89], 0, v[158:159]
	v_cvt_pk_bf16_f32 v88, v100, v101
	v_cvt_pk_bf16_f32 v89, v102, v103
	v_cvt_pk_bf16_f32 v90, v92, v93
	v_cvt_pk_bf16_f32 v91, v94, v95
	global_store_dwordx4 v[96:97], v[88:91], off
	v_cvt_pk_bf16_f32 v80, v80, v81
	v_cvt_pk_bf16_f32 v81, v82, v83
	v_cvt_pk_bf16_f32 v82, v72, v73
	v_or_b32_e32 v72, 48, v154
	v_ashrrev_i32_e32 v73, 31, v72
	v_lshlrev_b64 v[72:73], 13, v[72:73]
	v_lshl_add_u64 v[72:73], s[6:7], 0, v[72:73]
	v_cvt_pk_bf16_f32 v83, v74, v75
	global_store_dwordx4 v[96:97], v[80:83], off offset:256
	s_nop 1
	v_lshl_add_u64 v[80:81], v[72:73], 0, v[158:159]
	v_cvt_pk_bf16_f32 v72, v84, v85
	v_cvt_pk_bf16_f32 v73, v86, v87
	v_cvt_pk_bf16_f32 v74, v76, v77
	v_cvt_pk_bf16_f32 v75, v78, v79
	global_store_dwordx4 v[80:81], v[72:75], off
	v_cvt_pk_bf16_f32 v68, v68, v69
	v_cvt_pk_bf16_f32 v69, v70, v71
	v_cvt_pk_bf16_f32 v70, v64, v65
	v_cvt_pk_bf16_f32 v71, v66, v67
	global_store_dwordx4 v[80:81], v[68:71], off offset:256
	v_cvt_pk_bf16_f32 v60, v60, v61
	v_cvt_pk_bf16_f32 v61, v62, v63
	v_cvt_pk_bf16_f32 v62, v56, v57
	v_add_co_u32_e32 v56, vcc, s64, v144
	v_lshl_add_u64 v[64:65], v[144:145], 0, s[12:13]
	s_nop 0
	v_addc_co_u32_e32 v57, vcc, 0, v145, vcc
	v_cvt_pk_bf16_f32 v63, v58, v59
	global_store_dwordx4 v[56:57], v[60:63], off
	v_cvt_pk_bf16_f32 v48, v48, v49
	v_cvt_pk_bf16_f32 v49, v50, v51
	v_cvt_pk_bf16_f32 v50, v40, v41
	v_cvt_pk_bf16_f32 v51, v42, v43
	global_store_dwordx4 v[64:65], v[48:51], off offset:256
	v_cvt_pk_bf16_f32 v40, v52, v53
	v_cvt_pk_bf16_f32 v41, v54, v55
	v_cvt_pk_bf16_f32 v42, v44, v45
	v_add_co_u32_e32 v44, vcc, s65, v144
	s_nop 0
	v_lshl_add_u64 v[48:49], v[144:145], 0, s[14:15]
	v_addc_co_u32_e32 v45, vcc, 0, v145, vcc
	v_cvt_pk_bf16_f32 v43, v46, v47
	global_store_dwordx4 v[44:45], v[40:43], off
	v_cvt_pk_bf16_f32 v32, v32, v33
	v_cvt_pk_bf16_f32 v33, v34, v35
	v_cvt_pk_bf16_f32 v34, v24, v25
	v_cvt_pk_bf16_f32 v35, v26, v27
	global_store_dwordx4 v[48:49], v[32:35], off offset:256
	v_cvt_pk_bf16_f32 v24, v36, v37
	v_cvt_pk_bf16_f32 v25, v38, v39
	v_cvt_pk_bf16_f32 v26, v28, v29
	v_add_co_u32_e32 v28, vcc, s66, v144
	s_nop 0
	v_lshl_add_u64 v[32:33], v[144:145], 0, s[16:17]
	v_addc_co_u32_e32 v29, vcc, 0, v145, vcc
	v_cvt_pk_bf16_f32 v27, v30, v31
	global_store_dwordx4 v[28:29], v[24:27], off
	v_cvt_pk_bf16_f32 v16, v16, v17
	v_cvt_pk_bf16_f32 v17, v18, v19
	v_cvt_pk_bf16_f32 v18, v8, v9
	v_cvt_pk_bf16_f32 v19, v10, v11
	global_store_dwordx4 v[32:33], v[16:19], off offset:256
	v_cvt_pk_bf16_f32 v8, v20, v21
	v_cvt_pk_bf16_f32 v9, v22, v23
	v_cvt_pk_bf16_f32 v10, v12, v13
	v_add_co_u32_e32 v12, vcc, s67, v144
	s_nop 0
	v_lshl_add_u64 v[16:17], v[144:145], 0, s[18:19]
	v_addc_co_u32_e32 v13, vcc, 0, v145, vcc
	s_andn2_b64 vcc, exec, s[0:1]
	s_mov_b64 s[0:1], -1
	v_cvt_pk_bf16_f32 v11, v14, v15
	global_store_dwordx4 v[12:13], v[8:11], off
	v_cvt_pk_bf16_f32 v4, v4, v5
	v_cvt_pk_bf16_f32 v5, v6, v7
	v_cvt_pk_bf16_f32 v6, v0, v1
	v_cvt_pk_bf16_f32 v7, v2, v3
	global_store_dwordx4 v[16:17], v[4:7], off offset:256
	s_cbranch_vccz .Lp1_has_next
	s_andn2_b64 vcc, exec, s[4:5]
	s_cbranch_vccz .LBB0_112
	s_barrier
	s_branch .LBB0_112
.Lp1_has_next:
	s_barrier
	s_branch .LBB0_111
